# KT tile written with 8-byte stores after an in-register 8x16 transpose; pool_d two rows per thread
# speedup vs baseline: 1.0141x; 1.0041x over previous
; #define LAS __attribute__((address_space(3)))
; __device__ __forceinline__ float bflo(unsigned w) { return __uint_as_float(w << 16); }
; __device__ __forceinline__ float bfhi(unsigned w) { return __uint_as_float(w & 0xffff0000u); }
; __device__ __forceinline__ void conv16(const bf16_t* PROJ, const LAS float* cw, int rowbase, int t, int pcol, float (&y)[16]) {
;     u32x4 a[4], b[4];
; #pragma unroll
;     for (int i = 0; i < 4; ++i) {
;         const int tt = t - 3 + i, tc = tt < 0 ? 0 : tt;
;         a[i] = *(const u32x4*)(PROJ + (size_t)(rowbase + tc) * NQ + pcol); b[i] = *(const u32x4*)(PROJ + (size_t)(rowbase + tc) * NQ + pcol + 8);
;     }
; #pragma unroll
;     for (int j = 0; j < 16; ++j) y[j] = 0.f;
; #pragma unroll
;     for (int i = 0; i < 4; ++i) {
;         const float mk = (t - 3 + i) >= 0 ? 1.f : 0.f;
;         const f32x4 w0 = *(const LAS f32x4*)(cw + i * 128) * mk, w1 = *(const LAS f32x4*)(cw + i * 128 + 4) * mk, w2 = *(const LAS f32x4*)(cw + i * 128 + 8) * mk, w3 = *(const LAS f32x4*)(cw + i * 128 + 12) * mk;
;         y[0] += bflo(a[i].x) * w0.x; y[1] += bfhi(a[i].x) * w0.y; y[2] += bflo(a[i].y) * w0.z; y[3] += bfhi(a[i].y) * w0.w;
;         y[4] += bflo(a[i].z) * w1.x; y[5] += bfhi(a[i].z) * w1.y; y[6] += bflo(a[i].w) * w1.z; y[7] += bfhi(a[i].w) * w1.w;
;         y[8] += bflo(b[i].x) * w2.x; y[9] += bfhi(b[i].x) * w2.y; y[10] += bflo(b[i].y) * w2.z; y[11] += bfhi(b[i].y) * w2.w;
;         y[12] += bflo(b[i].z) * w3.x; y[13] += bfhi(b[i].z) * w3.y; y[14] += bflo(b[i].w) * w3.z; y[15] += bfhi(b[i].w) * w3.w;
;     }
; __device__ __forceinline__ void phase_chunk_prep(const Params& p, LAS unsigned char* lds, int wave_s) {
;     ...
;         const int r = tid >> 3, seg = tid & 7, t = t0 + r;
;         float q[16], k[16], v[16];
;         conv16(PROJ, CW + seg * 16, rowbase, t, 1024 + h * 128 + seg * 16, q);
;         conv16(PROJ, CW + 512 + seg * 16, rowbase, t, 1024 + 2048 + h * 128 + seg * 16, k);
;         conv16(PROJ, CW + 1024 + seg * 16, rowbase, t, 1024 + 4096 + h * 128 + seg * 16, v);
.LBB0_683:
	s_or_b64 exec, exec, s[4:5]
	v_lshrrev_b32_e32 v250, 3, v66
	v_lshlrev_b32_e32 v250, 8, v250
	v_and_b32_e32 v251, 7, v66
	v_lshl_add_u32 v250, v251, 5, v250
	v_add_u32_e32 v251, 0x1e200, v250
	s_ashr_i32 s17, s16, 31
	s_mul_i32 s5, s16, 0xec00
	s_mul_hi_i32 s4, s16, 0xec00
	s_add_u32 s30, s25, s5
	v_ashrrev_i32_e32 v67, 3, v66
	s_addc_u32 s31, s38, s4
	v_add_u32_e32 v90, s35, v67
	v_lshlrev_b32_e32 v0, 4, v66
	s_lshl_b32 s4, s78, 7
	v_and_b32_e32 v209, 0x70, v0
	s_add_i32 s5, s4, 0x400
	v_max_i32_e32 v0, 3, v90
	v_or_b32_e32 v2, s5, v209
	v_add3_u32 v215, s34, -3, v0
	s_waitcnt lgkmcnt(0)
	v_mov_b64_e32 v[4:5], s[28:29]
	v_mad_i64_i32 v[0:1], s[36:37], v215, s50, v[4:5]
	v_lshlrev_b32_e32 v64, 1, v2
	v_lshl_add_u64 v[124:125], v[0:1], 0, v[64:65]
	v_max_i32_e32 v0, 2, v90
	v_add3_u32 v214, s34, -2, v0
	v_mad_i64_i32 v[0:1], s[36:37], v214, s50, v[4:5]
	v_lshl_add_u64 v[2:3], v[0:1], 0, v[64:65]
	v_max_i32_e32 v0, 1, v90
	v_max_i32_e32 v6, 0, v90
	v_add3_u32 v213, s34, -1, v0
	v_add_u32_e32 v212, s34, v6
	s_add_i32 s5, s4, 0xc00
	v_mad_i64_i32 v[0:1], s[36:37], v213, s50, v[4:5]
	v_mad_i64_i32 v[4:5], s[34:35], v212, s50, v[4:5]
	v_or_b32_e32 v6, s5, v209
	v_lshl_add_u64 v[0:1], v[0:1], 0, v[64:65]
	v_lshl_add_u64 v[4:5], v[4:5], 0, v[64:65]
	v_lshlrev_b32_e32 v64, 1, v6
	v_lshl_add_u64 v[26:27], s[28:29], 0, v[64:65]
	v_mad_i64_i32 v[6:7], s[34:35], v215, s50, v[26:27]
	ds_read_b128 v[18:21], v250 offset:17408
	ds_read_b128 v[38:41], v250 offset:17424
	v_lshl_add_u32 v210, v209, 2, 0
	v_cmp_lt_i32_e32 vcc, 2, v90
	v_add_u32_e32 v91, 0x1ca00, v210
	v_add_u32_e32 v108, 0x1d200, v210
	v_cndmask_b32_e64 v10, 0, 1.0, vcc
	v_cmp_lt_i32_e32 vcc, 1, v90
	ds_read_b128 v[12:15], v91
	ds_read_b128 v[22:25], v91 offset:16
	ds_read_b128 v[28:31], v91 offset:32
	ds_read_b128 v[32:35], v91 offset:48
	ds_read_b128 v[42:45], v91 offset:512
	ds_read_b128 v[46:49], v91 offset:528
	ds_read_b128 v[50:53], v91 offset:544
	ds_read_b128 v[54:57], v91 offset:560
	ds_read_b128 v[58:61], v108
	ds_read_b128 v[68:71], v108 offset:16
	ds_read_b128 v[72:75], v108 offset:32
	ds_read_b128 v[76:79], v108 offset:48
	v_cndmask_b32_e64 v8, 0, 1.0, vcc
	s_waitcnt lgkmcnt(0)
	v_pk_mul_f32 v[146:147], v[8:9], v[42:43] op_sel_hi:[0,1]
	v_pk_mul_f32 v[168:169], v[8:9], v[44:45] op_sel_hi:[0,1]
	v_pk_mul_f32 v[176:177], v[8:9], v[46:47] op_sel_hi:[0,1]
	v_pk_mul_f32 v[184:185], v[8:9], v[48:49] op_sel_hi:[0,1]
	ds_read_b128 v[42:45], v108 offset:512
	ds_read_b128 v[46:49], v108 offset:528
	v_pk_mul_f32 v[106:107], v[10:11], v[32:33] op_sel_hi:[0,1]
	v_pk_mul_f32 v[32:33], v[10:11], v[74:75] op_sel_hi:[0,1]
	v_add_u32_e32 v74, 0x1da00, v210
	v_pk_mul_f32 v[126:127], v[10:11], v[14:15] op_sel_hi:[0,1]
	v_pk_mul_f32 v[102:103], v[10:11], v[30:31] op_sel_hi:[0,1]
	v_pk_mul_f32 v[188:189], v[8:9], v[50:51] op_sel_hi:[0,1]
	v_pk_mul_f32 v[192:193], v[8:9], v[52:53] op_sel_hi:[0,1]
	v_pk_mul_f32 v[196:197], v[8:9], v[54:55] op_sel_hi:[0,1]
	v_pk_mul_f32 v[98:99], v[8:9], v[56:57] op_sel_hi:[0,1]
	v_pk_mul_f32 v[88:89], v[10:11], v[60:61] op_sel_hi:[0,1]
	v_pk_mul_f32 v[118:119], v[10:11], v[58:59] op_sel_hi:[0,1]
	ds_read_b128 v[50:53], v108 offset:544
	s_waitcnt lgkmcnt(0)
	v_pk_mul_f32 v[100:101], v[8:9], v[44:45] op_sel_hi:[0,1]
	v_pk_mul_f32 v[132:133], v[8:9], v[42:43] op_sel_hi:[0,1]
	v_pk_mul_f32 v[182:183], v[10:11], v[24:25] op_sel_hi:[0,1]
	v_pk_mul_f32 v[6:7], v[10:11], v[34:35] op_sel_hi:[0,1]
	v_pk_mul_f32 v[84:85], v[8:9], v[50:51] op_sel_hi:[0,1]
	v_pk_mul_f32 v[144:145], v[10:11], v[12:13] op_sel_hi:[0,1]
	v_pk_mul_f32 v[138:139], v[10:11], v[22:23] op_sel_hi:[0,1]
	v_pk_mul_f32 v[120:121], v[10:11], v[28:29] op_sel_hi:[0,1]
	v_pk_mul_f32 v[16:17], v[10:11], v[70:71] op_sel_hi:[0,1]
	v_pk_mul_f32 v[22:23], v[10:11], v[68:69] op_sel_hi:[0,1]
	v_pk_mul_f32 v[12:13], v[10:11], v[72:73] op_sel_hi:[0,1]
	v_pk_mul_f32 v[36:37], v[10:11], v[78:79] op_sel_hi:[0,1]
	v_pk_mul_f32 v[28:29], v[10:11], v[76:77] op_sel_hi:[0,1]
	v_pk_mul_f32 v[68:69], v[8:9], v[52:53] op_sel_hi:[0,1]
	v_cmp_lt_i32_e32 vcc, 0, v90
	s_addk_i32 s4, 0x1400
	s_waitcnt lgkmcnt(0)
	v_lshlrev_b32_e32 v122, 16, v18
	v_lshlrev_b32_e32 v14, 16, v38
	v_and_b32_e32 v15, 0xffff0000, v38
	v_lshlrev_b32_e32 v54, 16, v39
	v_and_b32_e32 v55, 0xffff0000, v39
	v_lshlrev_b32_e32 v30, 16, v40
	v_and_b32_e32 v31, 0xffff0000, v40
	v_lshlrev_b32_e32 v38, 16, v41
	v_and_b32_e32 v39, 0xffff0000, v41
	ds_read_b128 v[40:43], v74
	v_pk_mul_f32 v[110:111], v[8:9], v[46:47] op_sel_hi:[0,1]
	ds_read_b128 v[44:47], v74 offset:16
	ds_read_b128 v[56:59], v74 offset:32
	ds_read_b128 v[60:63], v74 offset:48
	v_and_b32_e32 v123, 0xffff0000, v18
	v_lshlrev_b32_e32 v96, 16, v19
	s_waitcnt lgkmcnt(2)
	v_pk_mul_f32 v[104:105], v[10:11], v[46:47] op_sel_hi:[0,1]
	v_pk_mul_f32 v[130:131], v[10:11], v[44:45] op_sel_hi:[0,1]
	ds_read_b128 v[44:47], v108 offset:560
	v_and_b32_e32 v97, 0xffff0000, v19
	v_lshlrev_b32_e32 v24, 16, v20
	v_and_b32_e32 v25, 0xffff0000, v20
	v_lshlrev_b32_e32 v18, 16, v21
	v_and_b32_e32 v19, 0xffff0000, v21
	v_pk_mul_f32 v[20:21], v[8:9], v[48:49] op_sel_hi:[0,1]
	v_pk_mul_f32 v[148:149], v[10:11], v[42:43] op_sel_hi:[0,1]
	s_waitcnt lgkmcnt(0)
	v_pk_mul_f32 v[42:43], v[8:9], v[46:47] op_sel_hi:[0,1]
	v_pk_mul_f32 v[34:35], v[8:9], v[44:45] op_sel_hi:[0,1]
	ds_read_b128 v[44:47], v74 offset:512
	ds_read_b128 v[48:51], v74 offset:528
	v_pk_mul_f32 v[166:167], v[10:11], v[40:41] op_sel_hi:[0,1]
	v_pk_mul_f32 v[76:77], v[10:11], v[58:59] op_sel_hi:[0,1]
	v_pk_mul_f32 v[86:87], v[10:11], v[56:57] op_sel_hi:[0,1]
	s_waitcnt lgkmcnt(1)
	v_pk_mul_f32 v[156:157], v[8:9], v[46:47] op_sel_hi:[0,1]
	v_pk_mul_f32 v[172:173], v[8:9], v[44:45] op_sel_hi:[0,1]
	s_waitcnt lgkmcnt(0)
; #define LAS __attribute__((address_space(3)))
; __device__ __forceinline__ float bflo(unsigned w) { return __uint_as_float(w << 16); }
; __device__ __forceinline__ float bfhi(unsigned w) { return __uint_as_float(w & 0xffff0000u); }
; __device__ __forceinline__ void conv16(const bf16_t* PROJ, const LAS float* cw, int rowbase, int t, int pcol, float (&y)[16]) {
;     ...
;     for (int i = 0; i < 4; ++i) {
;         const float mk = (t - 3 + i) >= 0 ? 1.f : 0.f;
;         const f32x4 w0 = *(const LAS f32x4*)(cw + i * 128) * mk, w1 = *(const LAS f32x4*)(cw + i * 128 + 4) * mk, w2 = *(const LAS f32x4*)(cw + i * 128 + 8) * mk, w3 = *(const LAS f32x4*)(cw + i * 128 + 12) * mk;
;         y[0] += bflo(a[i].x) * w0.x; y[1] += bfhi(a[i].x) * w0.y; y[2] += bflo(a[i].y) * w0.z; y[3] += bfhi(a[i].y) * w0.w;
;         y[4] += bflo(a[i].z) * w1.x; y[5] += bfhi(a[i].z) * w1.y; y[6] += bflo(a[i].w) * w1.z; y[7] += bfhi(a[i].w) * w1.w;
;         y[8] += bflo(b[i].x) * w2.x; y[9] += bfhi(b[i].x) * w2.y; y[10] += bflo(b[i].y) * w2.z; y[11] += bfhi(b[i].y) * w2.w;
;         y[12] += bflo(b[i].z) * w3.x; y[13] += bfhi(b[i].z) * w3.y; y[14] += bflo(b[i].w) * w3.z; y[15] += bfhi(b[i].w) * w3.w;
;     }
	v_pk_mul_f32 v[116:117], v[8:9], v[50:51] op_sel_hi:[0,1]
	v_pk_mul_f32 v[142:143], v[8:9], v[48:49] op_sel_hi:[0,1]
	ds_read_b128 v[44:47], v74 offset:544
	ds_read_b128 v[48:51], v74 offset:560
	v_pk_mul_f32 v[40:41], v[10:11], v[62:63] op_sel_hi:[0,1]
	v_pk_mul_f32 v[60:61], v[10:11], v[60:61] op_sel_hi:[0,1]
	v_cndmask_b32_e64 v56, 0, 1.0, vcc
	s_waitcnt lgkmcnt(1)
	v_pk_mul_f32 v[80:81], v[8:9], v[46:47] op_sel_hi:[0,1]
	v_pk_mul_f32 v[94:95], v[8:9], v[44:45] op_sel_hi:[0,1]
	s_waitcnt lgkmcnt(0)
	v_pk_mul_f32 v[44:45], v[8:9], v[50:51] op_sel_hi:[0,1]
	v_pk_mul_f32 v[62:63], v[8:9], v[48:49] op_sel_hi:[0,1]
	ds_read_b128 v[8:11], v91 offset:1024
	ds_read_b128 v[46:49], v91 offset:1040
	v_cmp_lt_i32_e32 vcc, -1, v90
	v_pk_fma_f32 v[118:119], v[118:119], v[122:123], 0 op_sel_hi:[1,1,0]
	v_pk_fma_f32 v[12:13], v[12:13], v[14:15], 0 op_sel_hi:[1,1,0]
	s_waitcnt lgkmcnt(1)
	v_pk_mul_f32 v[186:187], v[56:57], v[8:9] op_sel_hi:[0,1]
	v_pk_mul_f32 v[198:199], v[56:57], v[10:11] op_sel_hi:[0,1]
	s_waitcnt lgkmcnt(0)
	v_pk_mul_f32 v[200:201], v[56:57], v[46:47] op_sel_hi:[0,1]
	v_pk_mul_f32 v[204:205], v[56:57], v[48:49] op_sel_hi:[0,1]
	ds_read_b128 v[8:11], v91 offset:1056
	ds_read_b128 v[46:49], v91 offset:1072
	v_cndmask_b32_e64 v64, 0, 1.0, vcc
	v_pk_fma_f32 v[36:37], v[36:37], v[38:39], 0 op_sel_hi:[1,1,0]
	s_waitcnt lgkmcnt(1)
	v_pk_mul_f32 v[232:233], v[56:57], v[8:9] op_sel_hi:[0,1]
	v_pk_mul_f32 v[234:235], v[56:57], v[10:11] op_sel_hi:[0,1]
	s_waitcnt lgkmcnt(0)
	v_pk_mul_f32 v[236:237], v[56:57], v[46:47] op_sel_hi:[0,1]
	v_pk_mul_f32 v[228:229], v[56:57], v[48:49] op_sel_hi:[0,1]
	ds_read_b128 v[8:11], v108 offset:1024
	ds_read_b128 v[46:49], v108 offset:1040
	s_waitcnt lgkmcnt(1)
	v_pk_mul_f32 v[158:159], v[56:57], v[10:11] op_sel_hi:[0,1]
	v_pk_mul_f32 v[170:171], v[56:57], v[8:9] op_sel_hi:[0,1]
	s_waitcnt lgkmcnt(0)
	v_pk_mul_f32 v[114:115], v[56:57], v[48:49] op_sel_hi:[0,1]
	v_pk_mul_f32 v[140:141], v[56:57], v[46:47] op_sel_hi:[0,1]
	ds_read_b128 v[8:11], v108 offset:1056
	ds_read_b128 v[46:49], v108 offset:1072
	s_waitcnt lgkmcnt(1)
	v_pk_mul_f32 v[72:73], v[56:57], v[10:11] op_sel_hi:[0,1]
	v_pk_mul_f32 v[92:93], v[56:57], v[8:9] op_sel_hi:[0,1]
	ds_read_b128 v[8:11], v74 offset:1024
	ds_read_b128 v[50:53], v74 offset:1040
	s_waitcnt lgkmcnt(2)
	v_pk_mul_f32 v[58:59], v[56:57], v[46:47] op_sel_hi:[0,1]
	v_pk_mul_f32 v[48:49], v[56:57], v[48:49] op_sel_hi:[0,1]
	s_waitcnt lgkmcnt(1)
	v_pk_mul_f32 v[164:165], v[56:57], v[10:11] op_sel_hi:[0,1]
	v_pk_mul_f32 v[180:181], v[56:57], v[8:9] op_sel_hi:[0,1]
	s_waitcnt lgkmcnt(0)
	v_pk_mul_f32 v[136:137], v[56:57], v[52:53] op_sel_hi:[0,1]
	v_pk_mul_f32 v[154:155], v[56:57], v[50:51] op_sel_hi:[0,1]
	ds_read_b128 v[8:11], v74 offset:1056
	ds_read_b128 v[50:53], v74 offset:1072
	s_waitcnt lgkmcnt(1)
	v_pk_mul_f32 v[82:83], v[56:57], v[10:11] op_sel_hi:[0,1]
	v_pk_mul_f32 v[112:113], v[56:57], v[8:9] op_sel_hi:[0,1]
	s_waitcnt lgkmcnt(0)
	v_pk_mul_f32 v[46:47], v[56:57], v[52:53] op_sel_hi:[0,1]
	v_pk_mul_f32 v[70:71], v[56:57], v[50:51] op_sel_hi:[0,1]
	ds_read_b128 v[8:11], v91 offset:1536
	ds_read_b128 v[50:53], v91 offset:1552
	s_waitcnt lgkmcnt(1)
	v_pk_mul_f32 v[194:195], v[64:65], v[8:9] op_sel_hi:[0,1]
	v_pk_mul_f32 v[202:203], v[64:65], v[10:11] op_sel_hi:[0,1]
	s_waitcnt lgkmcnt(0)
	v_pk_mul_f32 v[206:207], v[64:65], v[50:51] op_sel_hi:[0,1]
	v_pk_mul_f32 v[238:239], v[64:65], v[52:53] op_sel_hi:[0,1]
	ds_read_b128 v[8:11], v91 offset:1568
	ds_read_b128 v[50:53], v91 offset:1584
	s_waitcnt lgkmcnt(1)
	v_pk_mul_f32 v[240:241], v[64:65], v[8:9] op_sel_hi:[0,1]
	v_pk_mul_f32 v[242:243], v[64:65], v[10:11] op_sel_hi:[0,1]
	s_waitcnt lgkmcnt(0)
	v_pk_mul_f32 v[244:245], v[64:65], v[50:51] op_sel_hi:[0,1]
	v_pk_mul_f32 v[246:247], v[64:65], v[52:53] op_sel_hi:[0,1]
	ds_read_b128 v[8:11], v108 offset:1536
	ds_read_b128 v[50:53], v108 offset:1552
	s_waitcnt lgkmcnt(1)
	v_pk_mul_f32 v[162:163], v[64:65], v[10:11] op_sel_hi:[0,1]
	v_pk_mul_f32 v[178:179], v[64:65], v[8:9] op_sel_hi:[0,1]
	s_waitcnt lgkmcnt(0)
	v_pk_mul_f32 v[134:135], v[64:65], v[52:53] op_sel_hi:[0,1]
	v_pk_mul_f32 v[152:153], v[64:65], v[50:51] op_sel_hi:[0,1]
	ds_read_b128 v[8:11], v108 offset:1568
	ds_read_b128 v[50:53], v108 offset:1584
	s_waitcnt lgkmcnt(1)
	v_pk_mul_f32 v[78:79], v[64:65], v[10:11] op_sel_hi:[0,1]
	v_pk_mul_f32 v[108:109], v[64:65], v[8:9] op_sel_hi:[0,1]
	ds_read_b128 v[8:11], v74 offset:1536
	ds_read_b128 v[216:219], v74 offset:1552
	s_waitcnt lgkmcnt(2)
	v_pk_mul_f32 v[56:57], v[64:65], v[50:51] op_sel_hi:[0,1]
	v_pk_mul_f32 v[52:53], v[64:65], v[52:53] op_sel_hi:[0,1]
	s_waitcnt lgkmcnt(1)
	v_pk_mul_f32 v[174:175], v[64:65], v[10:11] op_sel_hi:[0,1]
	v_pk_mul_f32 v[190:191], v[64:65], v[8:9] op_sel_hi:[0,1]
	s_waitcnt lgkmcnt(0)
	v_pk_mul_f32 v[150:151], v[64:65], v[218:219] op_sel_hi:[0,1]
	v_pk_mul_f32 v[160:161], v[64:65], v[216:217] op_sel_hi:[0,1]
	ds_read_b128 v[8:11], v74 offset:1568
	ds_read_b128 v[216:219], v74 offset:1584
	s_waitcnt lgkmcnt(1)
	v_pk_mul_f32 v[128:129], v[64:65], v[8:9] op_sel_hi:[0,1]
	s_waitcnt lgkmcnt(0)
	v_pk_mul_f32 v[50:51], v[64:65], v[218:219] op_sel_hi:[0,1]
	v_pk_mul_f32 v[74:75], v[64:65], v[216:217] op_sel_hi:[0,1]
	ds_read_b128 v[216:219], v250 offset:16
	v_pk_mul_f32 v[90:91], v[64:65], v[10:11] op_sel_hi:[0,1]
	s_waitcnt lgkmcnt(0)
	v_lshlrev_b32_e32 v8, 16, v219
	v_and_b32_e32 v9, 0xffff0000, v219
	v_pk_fma_f32 v[6:7], v[6:7], v[8:9], 0 op_sel_hi:[1,1,0]
	ds_read_b128 v[220:223], v250 offset:272
	ds_read_b128 v[8:11], v250 offset:256
	s_waitcnt lgkmcnt(0)
; #define LAS __attribute__((address_space(3)))
; __device__ __forceinline__ float bflo(unsigned w) { return __uint_as_float(w << 16); }
; __device__ __forceinline__ float bfhi(unsigned w) { return __uint_as_float(w & 0xffff0000u); }
; __device__ __forceinline__ void conv16(const bf16_t* PROJ, const LAS float* cw, int rowbase, int t, int pcol, float (&y)[16]) {
;     ...
;     for (int i = 0; i < 4; ++i) {
;         const float mk = (t - 3 + i) >= 0 ? 1.f : 0.f;
;         const f32x4 w0 = *(const LAS f32x4*)(cw + i * 128) * mk, w1 = *(const LAS f32x4*)(cw + i * 128 + 4) * mk, w2 = *(const LAS f32x4*)(cw + i * 128 + 8) * mk, w3 = *(const LAS f32x4*)(cw + i * 128 + 12) * mk;
;         y[0] += bflo(a[i].x) * w0.x; y[1] += bfhi(a[i].x) * w0.y; y[2] += bflo(a[i].y) * w0.z; y[3] += bfhi(a[i].y) * w0.w;
;         y[4] += bflo(a[i].z) * w1.x; y[5] += bfhi(a[i].z) * w1.y; y[6] += bflo(a[i].w) * w1.z; y[7] += bfhi(a[i].w) * w1.w;
;         y[8] += bflo(b[i].x) * w2.x; y[9] += bfhi(b[i].x) * w2.y; y[10] += bflo(b[i].y) * w2.z; y[11] += bfhi(b[i].y) * w2.w;
;         y[12] += bflo(b[i].z) * w3.x; y[13] += bfhi(b[i].z) * w3.y; y[14] += bflo(b[i].w) * w3.z; y[15] += bfhi(b[i].w) * w3.w;
;     }
	v_lshlrev_b32_e32 v2, 16, v223
	v_and_b32_e32 v3, 0xffff0000, v223
	v_pk_fma_f32 v[6:7], v[98:99], v[2:3], v[6:7]
	ds_read_b128 v[224:227], v250 offset:528
	s_nop 0
	ds_read_b128 v[0:3], v250 offset:512
	v_and_b32_e32 v219, 0xffff0000, v222
	s_waitcnt lgkmcnt(0)
	v_lshlrev_b32_e32 v98, 16, v227
	v_and_b32_e32 v99, 0xffff0000, v227
	v_pk_fma_f32 v[98:99], v[228:229], v[98:99], v[6:7]
	ds_read_b128 v[228:231], v250 offset:784
	s_nop 0
	ds_read_b128 v[4:7], v250 offset:768
	s_waitcnt lgkmcnt(0)
	v_lshlrev_b32_e32 v248, 16, v231
	v_and_b32_e32 v249, 0xffff0000, v231
	v_pk_fma_f32 v[98:99], v[246:247], v[248:249], v[98:99]
	v_lshlrev_b32_e32 v246, 16, v218
	v_and_b32_e32 v247, 0xffff0000, v218
	v_pk_fma_f32 v[106:107], v[106:107], v[246:247], 0 op_sel_hi:[1,1,0]
	v_lshlrev_b32_e32 v218, 16, v222
	v_pk_fma_f32 v[106:107], v[196:197], v[218:219], v[106:107]
	v_lshlrev_b32_e32 v196, 16, v226
	v_and_b32_e32 v197, 0xffff0000, v226
	v_pk_fma_f32 v[106:107], v[236:237], v[196:197], v[106:107]
	v_lshlrev_b32_e32 v196, 16, v230
	v_and_b32_e32 v197, 0xffff0000, v230
	v_pk_fma_f32 v[106:107], v[244:245], v[196:197], v[106:107]
	v_lshlrev_b32_e32 v196, 16, v217
	v_and_b32_e32 v197, 0xffff0000, v217
	v_pk_fma_f32 v[102:103], v[102:103], v[196:197], 0 op_sel_hi:[1,1,0]
	v_lshlrev_b32_e32 v196, 16, v221
	v_and_b32_e32 v197, 0xffff0000, v221
	v_pk_fma_f32 v[102:103], v[192:193], v[196:197], v[102:103]
	v_lshlrev_b32_e32 v192, 16, v225
	v_and_b32_e32 v193, 0xffff0000, v225
	v_pk_fma_f32 v[102:103], v[234:235], v[192:193], v[102:103]
	v_lshlrev_b32_e32 v192, 16, v229
	v_and_b32_e32 v193, 0xffff0000, v229
	v_pk_fma_f32 v[102:103], v[242:243], v[192:193], v[102:103]
	v_lshlrev_b32_e32 v192, 16, v216
	v_and_b32_e32 v193, 0xffff0000, v216
	ds_read_b128 v[216:219], v250
	v_lshlrev_b32_e32 v196, 16, v220
	v_and_b32_e32 v197, 0xffff0000, v220
	v_pk_fma_f32 v[120:121], v[120:121], v[192:193], 0 op_sel_hi:[1,1,0]
	s_waitcnt lgkmcnt(0)
	v_lshlrev_b32_e32 v124, 16, v219
	v_and_b32_e32 v125, 0xffff0000, v219
	v_pk_fma_f32 v[124:125], v[182:183], v[124:125], 0 op_sel_hi:[1,1,0]
	v_lshlrev_b32_e32 v182, 16, v11
	v_and_b32_e32 v183, 0xffff0000, v11
	v_pk_fma_f32 v[124:125], v[184:185], v[182:183], v[124:125]
	v_lshlrev_b32_e32 v182, 16, v3
	v_and_b32_e32 v183, 0xffff0000, v3
	v_pk_fma_f32 v[124:125], v[204:205], v[182:183], v[124:125]
	v_lshlrev_b32_e32 v182, 16, v7
	v_and_b32_e32 v183, 0xffff0000, v7
	v_pk_fma_f32 v[124:125], v[238:239], v[182:183], v[124:125]
	v_lshlrev_b32_e32 v182, 16, v218
	v_and_b32_e32 v183, 0xffff0000, v218
	v_pk_fma_f32 v[138:139], v[138:139], v[182:183], 0 op_sel_hi:[1,1,0]
	v_lshlrev_b32_e32 v182, 16, v10
	v_and_b32_e32 v183, 0xffff0000, v10
	v_pk_fma_f32 v[10:11], v[176:177], v[182:183], v[138:139]
	v_lshlrev_b32_e32 v138, 16, v2
	v_and_b32_e32 v139, 0xffff0000, v2
	v_pk_fma_f32 v[2:3], v[200:201], v[138:139], v[10:11]
	v_lshlrev_b32_e32 v10, 16, v6
	v_and_b32_e32 v11, 0xffff0000, v6
	v_pk_fma_f32 v[138:139], v[206:207], v[10:11], v[2:3]
	v_lshlrev_b32_e32 v2, 16, v217
	v_and_b32_e32 v3, 0xffff0000, v217
	v_pk_fma_f32 v[2:3], v[126:127], v[2:3], 0 op_sel_hi:[1,1,0]
	v_lshlrev_b32_e32 v6, 16, v9
	v_and_b32_e32 v7, 0xffff0000, v9
	v_pk_fma_f32 v[2:3], v[168:169], v[6:7], v[2:3]
	v_lshlrev_b32_e32 v6, 16, v1
	v_and_b32_e32 v7, 0xffff0000, v1
	v_pk_fma_f32 v[2:3], v[198:199], v[6:7], v[2:3]
	v_lshlrev_b32_e32 v6, 16, v5
	v_and_b32_e32 v7, 0xffff0000, v5
	v_pk_fma_f32 v[126:127], v[202:203], v[6:7], v[2:3]
	v_lshlrev_b32_e32 v2, 16, v216
	v_and_b32_e32 v3, 0xffff0000, v216
	v_lshlrev_b32_e32 v6, 16, v8
	v_and_b32_e32 v7, 0xffff0000, v8
	v_pk_fma_f32 v[2:3], v[144:145], v[2:3], 0 op_sel_hi:[1,1,0]
	v_pk_fma_f32 v[120:121], v[188:189], v[196:197], v[120:121]
	v_pk_fma_f32 v[2:3], v[146:147], v[6:7], v[2:3]
	v_lshlrev_b32_e32 v6, 16, v0
	v_and_b32_e32 v7, 0xffff0000, v0
	v_pk_fma_f32 v[0:1], v[186:187], v[6:7], v[2:3]
	v_lshlrev_b32_e32 v2, 16, v4
	v_and_b32_e32 v3, 0xffff0000, v4
	v_pk_fma_f32 v[144:145], v[194:195], v[2:3], v[0:1]
	v_or_b32_e32 v0, s4, v209
	v_lshlrev_b32_e32 v64, 1, v0
	v_lshl_add_u64 v[146:147], s[28:29], 0, v[64:65]
	v_mad_i64_i32 v[4:5], s[4:5], v215, s50, v[146:147]
	ds_read_b128 v[0:3], v251
	v_lshlrev_b32_e32 v188, 16, v224
	v_and_b32_e32 v189, 0xffff0000, v224
	v_pk_fma_f32 v[120:121], v[232:233], v[188:189], v[120:121]
	v_lshlrev_b32_e32 v188, 16, v228
	v_and_b32_e32 v189, 0xffff0000, v228
	v_pk_fma_f32 v[120:121], v[240:241], v[188:189], v[120:121]
	v_lshlrev_b32_e32 v64, 1, v209
	s_waitcnt lgkmcnt(0)
	v_lshlrev_b32_e32 v6, 16, v0
	v_and_b32_e32 v7, 0xffff0000, v0
	v_pk_fma_f32 v[166:167], v[166:167], v[6:7], 0 op_sel_hi:[1,1,0]
	v_mad_i64_i32 v[6:7], s[4:5], v214, s50, v[146:147]
	ds_read_b128 v[8:11], v251 offset:256
	v_lshlrev_b32_e32 v0, 16, v1
	v_and_b32_e32 v1, 0xffff0000, v1
	v_pk_fma_f32 v[0:1], v[148:149], v[0:1], 0 op_sel_hi:[1,1,0]
	s_waitcnt lgkmcnt(0)
	v_lshlrev_b32_e32 v168, 16, v8
	v_and_b32_e32 v169, 0xffff0000, v8
	v_pk_fma_f32 v[168:169], v[172:173], v[168:169], v[166:167]
	v_mad_i64_i32 v[166:167], s[4:5], v213, s50, v[146:147]
	ds_read_b128 v[182:185], v251 offset:512
	v_lshlrev_b32_e32 v8, 16, v9
	v_and_b32_e32 v9, 0xffff0000, v9
	v_pk_fma_f32 v[0:1], v[156:157], v[8:9], v[0:1]
	s_waitcnt lgkmcnt(0)
	v_lshlrev_b32_e32 v172, 16, v182
	v_and_b32_e32 v173, 0xffff0000, v182
	v_pk_fma_f32 v[172:173], v[180:181], v[172:173], v[168:169]
	v_mad_i64_i32 v[168:169], s[4:5], v212, s50, v[146:147]
	ds_read_b128 v[186:189], v251 offset:768
	v_lshlrev_b32_e32 v8, 16, v183
	v_and_b32_e32 v9, 0xffff0000, v183
	v_pk_fma_f32 v[0:1], v[164:165], v[8:9], v[0:1]
	s_waitcnt lgkmcnt(0)
; #define LAS __attribute__((address_space(3)))
; __device__ __forceinline__ float bflo(unsigned w) { return __uint_as_float(w << 16); }
; __device__ __forceinline__ float bfhi(unsigned w) { return __uint_as_float(w & 0xffff0000u); }
; __device__ __forceinline__ float siluf_(float x) { return x * __builtin_amdgcn_rcpf(1.0f + __expf(-x)); }
; __device__ __forceinline__ void conv16(const bf16_t* PROJ, const LAS float* cw, int rowbase, int t, int pcol, float (&y)[16]) {
;     ...
;     for (int i = 0; i < 4; ++i) {
;         const float mk = (t - 3 + i) >= 0 ? 1.f : 0.f;
;         const f32x4 w0 = *(const LAS f32x4*)(cw + i * 128) * mk, w1 = *(const LAS f32x4*)(cw + i * 128 + 4) * mk, w2 = *(const LAS f32x4*)(cw + i * 128 + 8) * mk, w3 = *(const LAS f32x4*)(cw + i * 128 + 12) * mk;
;         y[0] += bflo(a[i].x) * w0.x; y[1] += bfhi(a[i].x) * w0.y; y[2] += bflo(a[i].y) * w0.z; y[3] += bfhi(a[i].y) * w0.w;
;         y[4] += bflo(a[i].z) * w1.x; y[5] += bfhi(a[i].z) * w1.y; y[6] += bflo(a[i].w) * w1.z; y[7] += bfhi(a[i].w) * w1.w;
;         y[8] += bflo(b[i].x) * w2.x; y[9] += bfhi(b[i].x) * w2.y; y[10] += bflo(b[i].y) * w2.z; y[11] += bfhi(b[i].y) * w2.w;
;         y[12] += bflo(b[i].z) * w3.x; y[13] += bfhi(b[i].z) * w3.y; y[14] += bflo(b[i].w) * w3.z; y[15] += bfhi(b[i].w) * w3.w;
;     }
; #pragma unroll
;     for (int j = 0; j < 16; ++j) y[j] = siluf_(y[j]);
	v_lshlrev_b32_e32 v146, 16, v186
	v_and_b32_e32 v147, 0xffff0000, v186
	v_pk_fma_f32 v[146:147], v[190:191], v[146:147], v[172:173]
	v_mad_i64_i32 v[172:173], s[4:5], v214, s50, v[26:27]
	ds_read_b128 v[190:193], v250 offset:17664
	v_lshlrev_b32_e32 v8, 16, v187
	v_and_b32_e32 v9, 0xffff0000, v187
	s_waitcnt lgkmcnt(0)
	v_lshlrev_b32_e32 v122, 16, v190
	v_and_b32_e32 v123, 0xffff0000, v190
	v_pk_fma_f32 v[118:119], v[132:133], v[122:123], v[118:119]
	v_mad_i64_i32 v[132:133], s[4:5], v213, s50, v[26:27]
	ds_read_b128 v[194:197], v250 offset:17920
	s_waitcnt lgkmcnt(0)
	v_lshlrev_b32_e32 v122, 16, v194
	v_and_b32_e32 v123, 0xffff0000, v194
	v_pk_fma_f32 v[118:119], v[170:171], v[122:123], v[118:119]
	v_mad_i64_i32 v[170:171], s[4:5], v212, s50, v[26:27]
	ds_read_b128 v[198:201], v250 offset:18176
	v_pk_fma_f32 v[122:123], v[174:175], v[8:9], v[0:1]
	v_pk_fma_f32 v[0:1], v[88:89], v[96:97], 0 op_sel_hi:[1,1,0]
	v_lshlrev_b32_e32 v8, 16, v191
	v_and_b32_e32 v9, 0xffff0000, v191
	v_pk_fma_f32 v[0:1], v[100:101], v[8:9], v[0:1]
	v_lshlrev_b32_e32 v8, 16, v195
	v_and_b32_e32 v9, 0xffff0000, v195
	v_pk_fma_f32 v[0:1], v[158:159], v[8:9], v[0:1]
	s_waitcnt lgkmcnt(0)
	v_lshlrev_b32_e32 v8, 16, v199
	v_and_b32_e32 v9, 0xffff0000, v199
	v_pk_fma_f32 v[88:89], v[162:163], v[8:9], v[0:1]
	v_lshlrev_b32_e32 v0, 16, v2
	v_and_b32_e32 v1, 0xffff0000, v2
	v_pk_fma_f32 v[0:1], v[130:131], v[0:1], 0 op_sel_hi:[1,1,0]
	v_lshlrev_b32_e32 v8, 16, v10
	v_and_b32_e32 v9, 0xffff0000, v10
	v_pk_fma_f32 v[0:1], v[142:143], v[8:9], v[0:1]
	v_lshlrev_b32_e32 v8, 16, v184
	v_and_b32_e32 v9, 0xffff0000, v184
	v_pk_fma_f32 v[0:1], v[154:155], v[8:9], v[0:1]
	v_lshlrev_b32_e32 v8, 16, v188
	v_and_b32_e32 v9, 0xffff0000, v188
	v_pk_fma_f32 v[96:97], v[160:161], v[8:9], v[0:1]
	v_pk_fma_f32 v[0:1], v[22:23], v[24:25], 0 op_sel_hi:[1,1,0]
	v_lshlrev_b32_e32 v8, 16, v192
	v_and_b32_e32 v9, 0xffff0000, v192
	v_pk_fma_f32 v[0:1], v[110:111], v[8:9], v[0:1]
	v_lshlrev_b32_e32 v8, 16, v196
	v_and_b32_e32 v9, 0xffff0000, v196
	v_pk_fma_f32 v[0:1], v[140:141], v[8:9], v[0:1]
	v_lshlrev_b32_e32 v8, 16, v200
	v_and_b32_e32 v9, 0xffff0000, v200
	v_pk_fma_f32 v[100:101], v[152:153], v[8:9], v[0:1]
	v_lshlrev_b32_e32 v0, 16, v3
	v_and_b32_e32 v1, 0xffff0000, v3
	v_lshlrev_b32_e32 v2, 16, v11
	v_and_b32_e32 v3, 0xffff0000, v11
	v_pk_fma_f32 v[0:1], v[104:105], v[0:1], 0 op_sel_hi:[1,1,0]
	ds_read_b128 v[8:11], v251 offset:272
	v_pk_fma_f32 v[0:1], v[116:117], v[2:3], v[0:1]
	v_lshlrev_b32_e32 v2, 16, v185
	v_and_b32_e32 v3, 0xffff0000, v185
	v_pk_fma_f32 v[0:1], v[136:137], v[2:3], v[0:1]
	v_lshlrev_b32_e32 v2, 16, v189
	v_and_b32_e32 v3, 0xffff0000, v189
	v_pk_fma_f32 v[104:105], v[150:151], v[2:3], v[0:1]
	v_lshlrev_b32_e32 v0, 16, v193
	v_and_b32_e32 v1, 0xffff0000, v193
	v_pk_fma_f32 v[2:3], v[16:17], v[18:19], 0 op_sel_hi:[1,1,0]
	v_lshlrev_b32_e32 v26, 16, v198
	v_pk_fma_f32 v[0:1], v[20:21], v[0:1], v[2:3]
	ds_read_b128 v[20:23], v251 offset:16
	v_lshlrev_b32_e32 v2, 16, v197
	ds_read_b128 v[4:7], v251 offset:528
	v_and_b32_e32 v3, 0xffff0000, v197
	v_pk_fma_f32 v[0:1], v[114:115], v[2:3], v[0:1]
	v_lshlrev_b32_e32 v2, 16, v201
	v_and_b32_e32 v3, 0xffff0000, v201
	v_pk_fma_f32 v[110:111], v[134:135], v[2:3], v[0:1]
	v_and_b32_e32 v27, 0xffff0000, v198
	v_pk_fma_f32 v[118:119], v[178:179], v[26:27], v[118:119]
	ds_read_b128 v[24:27], v250 offset:17680
	s_waitcnt lgkmcnt(0)
	v_lshlrev_b32_e32 v2, 16, v8
	v_and_b32_e32 v3, 0xffff0000, v8
	v_lshlrev_b32_e32 v8, 16, v9
	v_and_b32_e32 v9, 0xffff0000, v9
	s_waitcnt lgkmcnt(0)
	v_lshlrev_b32_e32 v0, 16, v20
	v_and_b32_e32 v1, 0xffff0000, v20
	v_pk_fma_f32 v[0:1], v[86:87], v[0:1], 0 op_sel_hi:[1,1,0]
	v_lshlrev_b32_e32 v20, 16, v21
	v_pk_fma_f32 v[0:1], v[94:95], v[2:3], v[0:1]
	s_waitcnt lgkmcnt(0)
	v_lshlrev_b32_e32 v2, 16, v4
	v_and_b32_e32 v3, 0xffff0000, v4
	v_pk_fma_f32 v[16:17], v[112:113], v[2:3], v[0:1]
	ds_read_b128 v[0:3], v251 offset:784
	v_and_b32_e32 v21, 0xffff0000, v21
	s_waitcnt lgkmcnt(0)
	v_lshlrev_b32_e32 v14, 16, v24
	v_and_b32_e32 v15, 0xffff0000, v24
	v_pk_fma_f32 v[20:21], v[76:77], v[20:21], 0 op_sel_hi:[1,1,0]
	v_lshlrev_b32_e32 v4, 16, v5
	v_pk_fma_f32 v[8:9], v[80:81], v[8:9], v[20:21]
	v_and_b32_e32 v5, 0xffff0000, v5
	v_pk_fma_f32 v[4:5], v[82:83], v[4:5], v[8:9]
	v_lshlrev_b32_e32 v20, 16, v25
	v_and_b32_e32 v21, 0xffff0000, v25
	s_waitcnt lgkmcnt(0)
	v_lshlrev_b32_e32 v18, 16, v0
	v_and_b32_e32 v19, 0xffff0000, v0
	v_pk_fma_f32 v[86:87], v[128:129], v[18:19], v[16:17]
	v_pk_fma_f32 v[16:17], v[84:85], v[14:15], v[12:13]
	ds_read_b128 v[12:15], v250 offset:17936
	v_lshlrev_b32_e32 v0, 16, v1
	v_and_b32_e32 v1, 0xffff0000, v1
	v_pk_fma_f32 v[80:81], v[90:91], v[0:1], v[4:5]
	v_mul_f32_e32 v0, 0xbfb8aa3b, v98
	v_mul_f32_e32 v1, 0xbfb8aa3b, v99
	v_exp_f32_e32 v0, v0
	v_exp_f32_e32 v1, v1
	v_mul_f32_e32 v4, 0xbfb8aa3b, v106
	v_exp_f32_e32 v8, v4
	v_add_f32_e32 v0, 1.0, v0
	v_add_f32_e32 v1, 1.0, v1
	v_mul_f32_e32 v4, 0xbfb8aa3b, v107
	v_rcp_f32_e32 v0, v0
	v_rcp_f32_e32 v1, v1
	v_exp_f32_e32 v9, v4
	v_pk_mul_f32 v[4:5], v[98:99], v[0:1]
	v_add_f32_e32 v0, 1.0, v8
	v_add_f32_e32 v1, 1.0, v9
	v_rcp_f32_e32 v0, v0
	v_rcp_f32_e32 v1, v1
	v_mul_f32_e32 v8, 0xbfb8aa3b, v102
	v_lshlrev_b32_e32 v98, 16, v23
	v_and_b32_e32 v99, 0xffff0000, v23
	v_pk_mul_f32 v[76:77], v[4:5], v[4:5]
	v_pk_fma_f32 v[40:41], v[40:41], v[98:99], 0 op_sel_hi:[1,1,0]
	s_waitcnt lgkmcnt(0)
	v_lshlrev_b32_e32 v18, 16, v12
	v_and_b32_e32 v19, 0xffff0000, v12
	v_pk_fma_f32 v[84:85], v[92:93], v[18:19], v[16:17]
	ds_read_b128 v[16:19], v250 offset:18192
	v_lshlrev_b32_e32 v12, 2, v211
	s_waitcnt lgkmcnt(0)
	s_barrier
; __device__ __forceinline__ float siluf_(float x) { return x * __builtin_amdgcn_rcpf(1.0f + __expf(-x)); }
; __device__ __forceinline__ float bperm(float v, int srclane) { return __builtin_bit_cast(float, __builtin_amdgcn_ds_bpermute(srclane << 2, __builtin_bit_cast(int, v))); }
; #define BAR_LDS() do { asm volatile("s_waitcnt lgkmcnt(0)" ::: "memory"); __builtin_amdgcn_s_barrier(); asm volatile("" ::: "memory"); } while (0)
; __device__ __forceinline__ void conv16(const bf16_t* PROJ, const LAS float* cw, int rowbase, int t, int pcol, float (&y)[16]) {
;     ...
;     for (int j = 0; j < 16; ++j) y[j] = siluf_(y[j]);
; __device__ __forceinline__ void phase_chunk_prep(const Params& p, LAS unsigned char* lds, int wave_s) {
;     ...
;         for (int j = 0; j < 16; ++j) { sq += q[j] * q[j]; sk += k[j] * k[j]; }
; #pragma unroll
;         for (int o = 1; o < 8; o <<= 1) { sq += bperm(sq, lane ^ o); sk += bperm(sk, lane ^ o); }
;         const float rq = rsqrtf(sq + EPS) * 0.08838834764831845f, rk = rsqrtf(sk + EPS);
; #pragma unroll
;         for (int j = 0; j < 16; ++j) { q[j] *= rq; k[j] *= rk; }
;         BAR_LDS();
;         const float gc_r = sgc[r], be_r = sbe[r], gc_last = sgc[63];
;         const float eg = __expf(gc_r), et = __expf(gc_last - gc_r);
	s_waitcnt vmcnt(0)
	v_lshlrev_b32_e32 v92, 16, v16
	v_and_b32_e32 v93, 0xffff0000, v16
	v_exp_f32_e32 v16, v8
	v_pk_mul_f32 v[8:9], v[106:107], v[0:1]
	v_mul_f32_e32 v0, 0xbfb8aa3b, v103
	v_pk_fma_f32 v[84:85], v[108:109], v[92:93], v[84:85]
	v_xor_b32_e32 v108, 4, v12
	v_xor_b32_e32 v106, 8, v12
	v_xor_b32_e32 v107, 16, v12
	v_add_f32_e32 v12, 1.0, v16
	v_exp_f32_e32 v16, v0
	v_pk_fma_f32 v[0:1], v[32:33], v[54:55], 0 op_sel_hi:[1,1,0]
	s_nop 0
	v_pk_fma_f32 v[0:1], v[68:69], v[20:21], v[0:1]
	v_rcp_f32_e32 v20, v12
	v_add_f32_e32 v12, 1.0, v16
	v_mul_f32_e32 v16, 0xbfb8aa3b, v120
	v_exp_f32_e32 v16, v16
	v_mul_f32_e32 v21, 0xbfb8aa3b, v121
	v_exp_f32_e32 v24, v21
	v_rcp_f32_e32 v21, v12
	v_add_f32_e32 v12, 1.0, v16
	v_rcp_f32_e32 v32, v12
	v_add_f32_e32 v12, 1.0, v24
	v_rcp_f32_e32 v33, v12
	v_mul_f32_e32 v12, 0xbfb8aa3b, v124
	v_exp_f32_e32 v12, v12
	v_pk_mul_f32 v[24:25], v[102:103], v[20:21]
	v_pk_mul_f32 v[54:55], v[120:121], v[32:33]
	v_pk_mul_f32 v[82:83], v[24:25], v[24:25]
	v_add_f32_e32 v16, 1.0, v12
	v_mul_f32_e32 v12, 0xbfb8aa3b, v125
	v_exp_f32_e32 v20, v12
	v_lshlrev_b32_e32 v12, 16, v13
	v_and_b32_e32 v13, 0xffff0000, v13
	v_pk_fma_f32 v[0:1], v[72:73], v[12:13], v[0:1]
	v_rcp_f32_e32 v12, v16
	v_mul_f32_e32 v16, 0xbfb8aa3b, v138
	v_add_f32_e32 v13, 1.0, v20
	v_exp_f32_e32 v16, v16
	v_mul_f32_e32 v20, 0xbfb8aa3b, v139
	v_exp_f32_e32 v21, v20
	v_rcp_f32_e32 v13, v13
	v_add_f32_e32 v16, 1.0, v16
	v_rcp_f32_e32 v20, v16
	v_add_f32_e32 v16, 1.0, v21
	v_rcp_f32_e32 v21, v16
	v_lshlrev_b32_e32 v16, 16, v17
	v_and_b32_e32 v17, 0xffff0000, v17
	v_pk_fma_f32 v[90:91], v[78:79], v[16:17], v[0:1]
	v_mul_f32_e32 v0, 0xbfb8aa3b, v126
	v_lshlrev_b32_e32 v16, 16, v10
	v_and_b32_e32 v17, 0xffff0000, v10
	v_mul_f32_e32 v10, 0xbfb8aa3b, v127
	v_pk_mul_f32 v[68:69], v[138:139], v[20:21]
	v_exp_f32_e32 v20, v0
	v_exp_f32_e32 v10, v10
	v_lshlrev_b32_e32 v0, 16, v22
	v_and_b32_e32 v1, 0xffff0000, v22
	v_pk_fma_f32 v[0:1], v[60:61], v[0:1], 0 op_sel_hi:[1,1,0]
	v_add_f32_e32 v22, 1.0, v20
	v_pk_fma_f32 v[0:1], v[62:63], v[16:17], v[0:1]
	v_lshlrev_b32_e32 v16, 16, v6
	v_and_b32_e32 v17, 0xffff0000, v6
	v_mul_f32_e32 v6, 0xbfb8aa3b, v144
	v_pk_fma_f32 v[20:21], v[70:71], v[16:17], v[0:1]
	v_add_f32_e32 v1, 1.0, v10
	v_exp_f32_e32 v6, v6
	v_mul_f32_e32 v10, 0xbfb8aa3b, v145
	v_exp_f32_e32 v10, v10
	v_rcp_f32_e32 v0, v22
	v_rcp_f32_e32 v1, v1
	v_add_f32_e32 v6, 1.0, v6
	v_rcp_f32_e32 v32, v6
	v_add_f32_e32 v6, 1.0, v10
	v_rcp_f32_e32 v33, v6
	v_lshl_add_u32 v6, v67, 2, 0
	v_add_u32_e32 v10, 0x1c800, v6
	v_pk_mul_f32 v[16:17], v[126:127], v[0:1]
	v_mov_b32_e32 v1, s51
	v_add_u32_e32 v6, 0x1c900, v6
	ds_read_b32 v10, v10
	ds_read_b32 v0, v6
	ds_read_b32 v1, v1
	v_pk_mul_f32 v[60:61], v[144:145], v[32:33]
	v_lshlrev_b32_e32 v32, 16, v2
	v_and_b32_e32 v33, 0xffff0000, v2
	s_waitcnt lgkmcnt(2)
	v_mul_f32_e32 v2, 0x3fb8aa3b, v10
	s_waitcnt lgkmcnt(0)
	v_sub_f32_e32 v6, v1, v10
	v_mul_lo_u32 v10, v67, s56
	v_add3_u32 v102, 0, v10, v64
	v_mul_f32_e32 v10, 0xbfb8aa3b, v146
	v_exp_f32_e32 v10, v10
	v_mul_f32_e32 v22, 0xbfb8aa3b, v147
	v_exp_f32_e32 v22, v22
	v_pk_fma_f32 v[92:93], v[74:75], v[32:33], v[20:21]
	v_pk_fma_f32 v[20:21], v[28:29], v[30:31], 0 op_sel_hi:[1,1,0]
	v_lshlrev_b32_e32 v28, 16, v26
	v_and_b32_e32 v29, 0xffff0000, v26
	v_pk_fma_f32 v[20:21], v[34:35], v[28:29], v[20:21]
	v_lshlrev_b32_e32 v28, 16, v14
	v_and_b32_e32 v29, 0xffff0000, v14
	v_add_f32_e32 v10, 1.0, v10
	v_mul_f32_e32 v14, 0xbfb8aa3b, v118
	v_pk_fma_f32 v[20:21], v[58:59], v[28:29], v[20:21]
	v_rcp_f32_e32 v28, v10
	v_add_f32_e32 v10, 1.0, v22
	v_exp_f32_e32 v14, v14
	v_mul_f32_e32 v22, 0xbfb8aa3b, v119
	v_exp_f32_e32 v22, v22
	v_rcp_f32_e32 v29, v10
	v_add_f32_e32 v10, 1.0, v14
	v_mul_f32_e32 v14, 0xbfb8aa3b, v122
	v_rcp_f32_e32 v30, v10
	v_add_f32_e32 v10, 1.0, v22
	v_exp_f32_e32 v14, v14
	v_mul_f32_e32 v22, 0xbfb8aa3b, v123
	v_exp_f32_e32 v22, v22
	v_rcp_f32_e32 v31, v10
	v_add_f32_e32 v10, 1.0, v14
	v_rcp_f32_e32 v34, v10
	v_add_f32_e32 v10, 1.0, v22
	v_rcp_f32_e32 v35, v10
	v_mul_f32_e32 v10, 0xbfb8aa3b, v88
	v_exp_f32_e32 v10, v10
	v_mul_f32_e32 v14, 0xbfb8aa3b, v89
	v_exp_f32_e32 v14, v14
	v_pk_mul_f32 v[58:59], v[118:119], v[30:31]
	v_add_f32_e32 v10, 1.0, v10
	v_pk_mul_f32 v[30:31], v[122:123], v[34:35]
	v_rcp_f32_e32 v34, v10
	v_add_f32_e32 v10, 1.0, v14
	v_rcp_f32_e32 v35, v10
	v_mul_f32_e32 v10, 0xbfb8aa3b, v96
	v_exp_f32_e32 v10, v10
	v_mul_f32_e32 v14, 0xbfb8aa3b, v97
	v_exp_f32_e32 v14, v14
	v_pk_mul_f32 v[62:63], v[88:89], v[34:35]
	v_add_f32_e32 v10, 1.0, v10
	v_rcp_f32_e32 v34, v10
	v_add_f32_e32 v10, 1.0, v14
	v_mul_f32_e32 v14, 0xbfb8aa3b, v100
	v_exp_f32_e32 v14, v14
	v_mul_f32_e32 v22, 0xbfb8aa3b, v101
	v_exp_f32_e32 v22, v22
	v_rcp_f32_e32 v35, v10
	v_add_f32_e32 v10, 1.0, v14
	v_mul_f32_e32 v14, 0xbfb8aa3b, v104
	v_rcp_f32_e32 v70, v10
	v_add_f32_e32 v10, 1.0, v22
	v_exp_f32_e32 v14, v14
	v_mul_f32_e32 v22, 0xbfb8aa3b, v105
	v_exp_f32_e32 v22, v22
	v_rcp_f32_e32 v71, v10
	v_add_f32_e32 v10, 1.0, v14
	v_rcp_f32_e32 v74, v10
	v_add_f32_e32 v10, 1.0, v22
	v_rcp_f32_e32 v75, v10
	v_mul_f32_e32 v10, 0xbfb8aa3b, v110
	v_exp_f32_e32 v10, v10
	v_mul_f32_e32 v14, 0xbfb8aa3b, v111
	v_exp_f32_e32 v14, v14
	v_mul_lo_u32 v32, v67, s57
	v_ashrrev_i32_e32 v33, 31, v32
	v_pk_mul_f32 v[34:35], v[96:97], v[34:35]
	v_add_f32_e32 v10, 1.0, v10
	v_lshl_add_u64 v[88:89], v[32:33], 1, s[30:31]
	v_pk_mul_f32 v[32:33], v[34:35], v[0:1] op_sel_hi:[1,0]
	v_pk_mul_f32 v[34:35], v[104:105], v[74:75]
	v_rcp_f32_e32 v74, v10
	v_add_f32_e32 v10, 1.0, v14
	v_mul_f32_e32 v14, 0xbfb8aa3b, v86
	v_exp_f32_e32 v14, v14
	v_mul_f32_e32 v22, 0xbfb8aa3b, v87
	v_exp_f32_e32 v22, v22
; __device__ __forceinline__ float siluf_(float x) { return x * __builtin_amdgcn_rcpf(1.0f + __expf(-x)); }
; __device__ __forceinline__ float bperm(float v, int srclane) { return __builtin_bit_cast(float, __builtin_amdgcn_ds_bpermute(srclane << 2, __builtin_bit_cast(int, v))); }
; __device__ __forceinline__ void conv16(const bf16_t* PROJ, const LAS float* cw, int rowbase, int t, int pcol, float (&y)[16]) {
;     ...
;     for (int j = 0; j < 16; ++j) y[j] = siluf_(y[j]);
; __device__ __forceinline__ void phase_chunk_prep(const Params& p, LAS unsigned char* lds, int wave_s) {
;     ...
;         for (int j = 0; j < 16; ++j) { sq += q[j] * q[j]; sk += k[j] * k[j]; }
; #pragma unroll
;         for (int o = 1; o < 8; o <<= 1) { sq += bperm(sq, lane ^ o); sk += bperm(sk, lane ^ o); }
	v_rcp_f32_e32 v75, v10
	v_add_f32_e32 v10, 1.0, v14
	v_mul_f32_e32 v14, 0xbfb8aa3b, v84
	v_rcp_f32_e32 v94, v10
	v_add_f32_e32 v10, 1.0, v22
	v_exp_f32_e32 v14, v14
	v_mul_f32_e32 v22, 0xbfb8aa3b, v85
	v_exp_f32_e32 v22, v22
	v_rcp_f32_e32 v95, v10
	v_add_f32_e32 v10, 1.0, v14
	v_rcp_f32_e32 v96, v10
	v_add_f32_e32 v10, 1.0, v22
	v_rcp_f32_e32 v97, v10
	v_mov_b32_e32 v22, v59
	v_mov_b32_e32 v23, v61
	v_pk_mul_f32 v[22:23], v[22:23], v[22:23]
	v_pk_mul_f32 v[84:85], v[84:85], v[96:97]
	v_lshlrev_b32_e32 v96, 16, v18
	v_and_b32_e32 v97, 0xffff0000, v18
	v_pk_fma_f32 v[56:57], v[56:57], v[96:97], v[20:21]
	v_mov_b32_e32 v20, v58
	v_mov_b32_e32 v21, v60
	v_mul_f32_e32 v10, 0xbfb8aa3b, v80
	v_pk_fma_f32 v[20:21], v[20:21], v[20:21], v[22:23]
	v_mov_b32_e32 v22, v62
	v_mov_b32_e32 v23, v16
	v_exp_f32_e32 v10, v10
	v_mul_f32_e32 v14, 0xbfb8aa3b, v81
	v_pk_mul_f32 v[70:71], v[100:101], v[70:71]
	v_pk_fma_f32 v[20:21], v[22:23], v[22:23], v[20:21]
	v_mov_b32_e32 v22, v63
	v_mov_b32_e32 v23, v17
	v_exp_f32_e32 v14, v14
	v_pk_fma_f32 v[20:21], v[22:23], v[22:23], v[20:21]
	v_mov_b32_e32 v22, v70
	v_mov_b32_e32 v23, v68
	v_pk_mul_f32 v[12:13], v[124:125], v[12:13]
	v_pk_mul_f32 v[74:75], v[110:111], v[74:75]
	v_pk_fma_f32 v[20:21], v[22:23], v[22:23], v[20:21]
	v_mov_b32_e32 v22, v71
	v_mov_b32_e32 v23, v69
	v_pk_fma_f32 v[20:21], v[22:23], v[22:23], v[20:21]
	v_mov_b32_e32 v22, v74
	v_mov_b32_e32 v23, v12
	v_add_f32_e32 v10, 1.0, v10
	v_pk_fma_f32 v[20:21], v[22:23], v[22:23], v[20:21]
	v_rcp_f32_e32 v22, v10
	v_add_f32_e32 v10, 1.0, v14
	v_rcp_f32_e32 v23, v10
	v_mul_f32_e32 v10, 0xbfb8aa3b, v90
	v_exp_f32_e32 v10, v10
	v_mul_f32_e32 v14, 0xbfb8aa3b, v91
	v_exp_f32_e32 v14, v14
	v_pk_mul_f32 v[22:23], v[80:81], v[22:23]
	v_add_f32_e32 v10, 1.0, v10
	v_rcp_f32_e32 v80, v10
	v_add_f32_e32 v10, 1.0, v14
	v_mul_f32_e32 v14, 0xbfb8aa3b, v92
	v_exp_f32_e32 v14, v14
	v_mul_f32_e32 v18, 0xbfb8aa3b, v93
	v_exp_f32_e32 v18, v18
	v_pk_mul_f32 v[78:79], v[54:55], v[54:55]
	v_pk_mul_f32 v[96:97], v[84:85], v[84:85]
	v_mov_b32_e32 v100, v75
	v_mov_b32_e32 v101, v13
	v_pk_mul_f32 v[94:95], v[86:87], v[94:95]
	v_pk_fma_f32 v[20:21], v[100:101], v[100:101], v[20:21]
	v_mov_b32_e32 v100, v96
	v_mov_b32_e32 v101, v78
	v_rcp_f32_e32 v81, v10
	v_add_f32_e32 v10, 1.0, v14
	v_mul_f32_e32 v14, 0xbfb8aa3b, v56
	v_pk_add_f32 v[100:101], v[100:101], v[20:21]
	v_pk_mul_f32 v[20:21], v[94:95], v[0:1] op_sel_hi:[1,0]
	v_rcp_f32_e32 v94, v10
	v_add_f32_e32 v10, 1.0, v18
	v_exp_f32_e32 v14, v14
	v_mul_f32_e32 v18, 0xbfb8aa3b, v57
	v_exp_f32_e32 v18, v18
	v_lshlrev_b32_e32 v26, 16, v27
	v_and_b32_e32 v27, 0xffff0000, v27
	v_rcp_f32_e32 v95, v10
	v_add_f32_e32 v10, 1.0, v14
	v_pk_fma_f32 v[26:27], v[42:43], v[26:27], v[36:37]
	v_lshlrev_b32_e32 v14, 16, v15
	v_and_b32_e32 v15, 0xffff0000, v15
	v_pk_mul_f32 v[80:81], v[90:91], v[80:81]
	v_rcp_f32_e32 v90, v10
	v_add_f32_e32 v10, 1.0, v18
	v_pk_fma_f32 v[14:15], v[48:49], v[14:15], v[26:27]
	v_lshlrev_b32_e32 v18, 16, v19
	v_and_b32_e32 v19, 0xffff0000, v19
	v_pk_fma_f32 v[14:15], v[52:53], v[18:19], v[14:15]
	v_rcp_f32_e32 v91, v10
	v_mul_f32_e32 v18, 0xbfb8aa3b, v14
	v_mul_f32_e32 v19, 0xbfb8aa3b, v15
	v_exp_f32_e32 v18, v18
	v_exp_f32_e32 v19, v19
	v_pk_mul_f32 v[92:93], v[92:93], v[94:95]
	v_pk_mul_f32 v[94:95], v[80:81], v[80:81]
	v_add_f32_e32 v18, 1.0, v18
	v_add_f32_e32 v19, 1.0, v19
	v_rcp_f32_e32 v18, v18
	v_rcp_f32_e32 v19, v19
	v_mov_b32_e32 v78, v97
	v_pk_mul_f32 v[56:57], v[56:57], v[90:91]
	v_pk_add_f32 v[36:37], v[78:79], v[100:101]
	v_mov_b32_e32 v38, v94
	v_mov_b32_e32 v39, v82
	v_pk_mul_f32 v[72:73], v[8:9], v[8:9]
	v_pk_mul_f32 v[90:91], v[56:57], v[56:57]
	v_pk_add_f32 v[36:37], v[38:39], v[36:37]
	v_mov_b32_e32 v82, v95
	v_pk_mul_f32 v[18:19], v[14:15], v[18:19]
	v_pk_add_f32 v[36:37], v[82:83], v[36:37]
	v_mov_b32_e32 v38, v90
	v_mov_b32_e32 v39, v72
	v_pk_mul_f32 v[14:15], v[18:19], v[18:19]
	v_pk_add_f32 v[36:37], v[38:39], v[36:37]
	v_mov_b32_e32 v72, v91
	v_pk_add_f32 v[36:37], v[72:73], v[36:37]
	v_mov_b32_e32 v38, v14
	v_mov_b32_e32 v39, v76
	v_pk_add_f32 v[36:37], v[38:39], v[36:37]
	v_mov_b32_e32 v76, v15
	v_pk_add_f32 v[14:15], v[76:77], v[36:37]
	ds_bpermute_b32 v37, v108, v15
	ds_bpermute_b32 v36, v108, v14
	v_lshlrev_b32_e32 v10, 16, v11
	v_and_b32_e32 v11, 0xffff0000, v11
	v_pk_fma_f32 v[10:11], v[44:45], v[10:11], v[40:41]
	v_lshlrev_b32_e32 v26, 16, v7
	v_and_b32_e32 v27, 0xffff0000, v7
	v_pk_fma_f32 v[10:11], v[46:47], v[26:27], v[10:11]
	v_lshlrev_b32_e32 v26, 16, v3
	v_and_b32_e32 v27, 0xffff0000, v3
	s_waitcnt lgkmcnt(0)
	v_pk_add_f32 v[14:15], v[14:15], v[36:37]
	v_pk_fma_f32 v[10:11], v[50:51], v[26:27], v[10:11]
	ds_bpermute_b32 v27, v106, v15
	ds_bpermute_b32 v26, v106, v14
	v_mul_f32_e32 v3, 0xbfb8aa3b, v10
	v_exp_f32_e32 v3, v3
	v_mul_f32_e32 v7, 0xbfb8aa3b, v11
	v_exp_f32_e32 v7, v7
	s_waitcnt lgkmcnt(0)
	v_pk_add_f32 v[14:15], v[14:15], v[26:27]
	ds_bpermute_b32 v27, v107, v15
	ds_bpermute_b32 v26, v107, v14
	v_add_f32_e32 v3, 1.0, v3
	v_rcp_f32_e32 v38, v3
	v_add_f32_e32 v3, 1.0, v7
	v_rcp_f32_e32 v39, v3
	s_waitcnt lgkmcnt(0)
; #define LAS __attribute__((address_space(3)))
; __device__ __forceinline__ unsigned pk2(float lo, float hi) { const f32x2_t v = {lo, hi}; const bf16x2_t b = __builtin_convertvector(v, bf16x2_t); return __builtin_bit_cast(unsigned, b); }
; #define BAR_LDS() do { asm volatile("s_waitcnt lgkmcnt(0)" ::: "memory"); __builtin_amdgcn_s_barrier(); asm volatile("" ::: "memory"); } while (0)
; __device__ __forceinline__ void phase_chunk_prep(const Params& p, LAS unsigned char* lds, int wave_s) {
;     ...
;         const float rq = rsqrtf(sq + EPS) * 0.08838834764831845f, rk = rsqrtf(sk + EPS);
; #pragma unroll
;         for (int j = 0; j < 16; ++j) { q[j] *= rq; k[j] *= rk; }
;         BAR_LDS();
;         const float gc_r = sgc[r], be_r = sbe[r], gc_last = sgc[63];
;         const float eg = __expf(gc_r), et = __expf(gc_last - gc_r);
;         {
;             u32x4 w0, w1;
;             w0.x = pk2(k[0], k[1]); w0.y = pk2(k[2], k[3]); w0.z = pk2(k[4], k[5]); w0.w = pk2(k[6], k[7]);
;             w1.x = pk2(k[8], k[9]); w1.y = pk2(k[10], k[11]); w1.z = pk2(k[12], k[13]); w1.w = pk2(k[14], k[15]);
;             *(LAS u32x4*)(KN + r * 136 + seg * 16) = w0; *(LAS u32x4*)(KN + r * 136 + seg * 16 + 8) = w1;
;             w0.x = pk2(q[0], q[1]); w0.y = pk2(q[2], q[3]); w0.z = pk2(q[4], q[5]); w0.w = pk2(q[6], q[7]);
;             w1.x = pk2(q[8], q[9]); w1.y = pk2(q[10], q[11]); w1.z = pk2(q[12], q[13]); w1.w = pk2(q[14], q[15]);
;             *(LAS u32x4*)(QN + r * 136 + seg * 16) = w0; *(LAS u32x4*)(QN + r * 136 + seg * 16 + 8) = w1;
;             w0.x = pk2(q[0] * eg, q[1] * eg); w0.y = pk2(q[2] * eg, q[3] * eg); w0.z = pk2(q[4] * eg, q[5] * eg); w0.w = pk2(q[6] * eg, q[7] * eg);
;             w1.x = pk2(q[8] * eg, q[9] * eg); w1.y = pk2(q[10] * eg, q[11] * eg); w1.z = pk2(q[12] * eg, q[13] * eg); w1.w = pk2(q[14] * eg, q[15] * eg);
;             { bf16_t* qd = img + IMG_QD + r * SWD + seg * 16;
;               *(u32x2*)(qd) = (u32x2){w0.x, w0.y}; *(u32x2*)(qd + 4) = (u32x2){w0.z, w0.w}; *(u32x2*)(qd + 8) = (u32x2){w1.x, w1.y}; *(u32x2*)(qd + 12) = (u32x2){w1.z, w1.w}; }
;         }
; #pragma unroll
;         for (int j = 0; j < 16; ++j) { RHS[r * 256 + seg * 16 + j] = v[j] * be_r; RHS[r * 256 + 128 + seg * 16 + j] = k[j] * be_r * eg; }
	v_pk_add_f32 v[14:15], v[14:15], v[26:27]
	v_exp_f32_e32 v2, v2
	v_pk_add_f32 v[26:27], v[14:15], s[14:15] op_sel_hi:[1,0]
	v_pk_mul_f32 v[10:11], v[10:11], v[38:39]
	v_mul_f32_e32 v3, 0x4b800000, v27
	v_cmp_gt_f32_e32 vcc, s58, v27
	v_pk_mul_f32 v[38:39], v[10:11], v[0:1] op_sel_hi:[1,0]
	v_lshl_add_u64 v[88:89], v[88:89], 0, v[64:65]
	v_cndmask_b32_e32 v3, v27, v3, vcc
	v_rsq_f32_e32 v3, v3
	v_lshl_add_u64 v[86:87], v[88:89], 0, s[12:13]
	v_lshl_add_u32 v64, v67, 10, v210
	v_mul_f32_e32 v6, 0x3fb8aa3b, v6
	v_mul_f32_e32 v7, 0x45800000, v3
	v_cndmask_b32_e32 v3, v3, v7, vcc
	v_mul_f32_e32 v10, 0x3db504f3, v3
	v_pk_mul_f32 v[40:41], v[60:61], v[10:11] op_sel_hi:[1,0]
	v_pk_mul_f32 v[16:17], v[16:17], v[10:11] op_sel_hi:[1,0]
	v_pk_mul_f32 v[42:43], v[68:69], v[10:11] op_sel_hi:[1,0]
	v_pk_mul_f32 v[44:45], v[12:13], v[10:11] op_sel_hi:[1,0]
	v_pk_mul_f32 v[46:47], v[54:55], v[10:11] op_sel_hi:[1,0]
	v_pk_mul_f32 v[24:25], v[24:25], v[10:11] op_sel_hi:[1,0]
	v_pk_mul_f32 v[48:49], v[8:9], v[10:11] op_sel_hi:[1,0]
	v_pk_mul_f32 v[4:5], v[4:5], v[10:11] op_sel_hi:[1,0]
	v_cvt_pk_bf16_f32 v8, v40, v41
	v_cvt_pk_bf16_f32 v9, v16, v17
	v_cvt_pk_bf16_f32 v10, v42, v43
	v_cvt_pk_bf16_f32 v11, v44, v45
	v_cvt_pk_bf16_f32 v12, v46, v47
	v_cvt_pk_bf16_f32 v13, v24, v25
	v_cvt_pk_bf16_f32 v14, v48, v49
	v_cvt_pk_bf16_f32 v15, v4, v5
	ds_write_b128 v102, v[8:11] offset:17408
	ds_write_b128 v102, v[12:15] offset:17424
	v_pk_mul_f32 v[8:9], v[2:3], v[40:41] op_sel_hi:[0,1]
	v_pk_mul_f32 v[10:11], v[2:3], v[16:17] op_sel_hi:[0,1]
	v_cvt_pk_bf16_f32 v8, v8, v9
	v_cvt_pk_bf16_f32 v9, v10, v11
	v_pk_mul_f32 v[10:11], v[2:3], v[42:43] op_sel_hi:[0,1]
	v_pk_mul_f32 v[12:13], v[2:3], v[44:45] op_sel_hi:[0,1]
	v_cvt_pk_bf16_f32 v10, v10, v11
	v_cvt_pk_bf16_f32 v11, v12, v13
	v_pk_mul_f32 v[12:13], v[2:3], v[46:47] op_sel_hi:[0,1]
	v_pk_mul_f32 v[14:15], v[2:3], v[24:25] op_sel_hi:[0,1]
	v_cvt_pk_bf16_f32 v12, v12, v13
	v_cvt_pk_bf16_f32 v13, v14, v15
	v_pk_mul_f32 v[14:15], v[2:3], v[48:49] op_sel_hi:[0,1]
	v_pk_mul_f32 v[4:5], v[2:3], v[4:5] op_sel_hi:[0,1]
	v_mul_f32_e32 v3, 0x4b800000, v26
	v_cmp_gt_f32_e32 vcc, s58, v26
	v_cvt_pk_bf16_f32 v14, v14, v15
	v_cvt_pk_bf16_f32 v15, v4, v5
	v_cndmask_b32_e32 v3, v26, v3, vcc
	v_rsq_f32_e32 v3, v3
	v_add_co_u32_e64 v4, s[4:5], s47, v88
	v_pk_mul_f32 v[28:29], v[146:147], v[28:29]
	s_nop 0
	v_addc_co_u32_e64 v5, s[4:5], 0, v89, s[4:5]
	global_store_dwordx4 v[4:5], v[8:11], off offset:512
	global_store_dwordx4 v[86:87], v[12:15], off offset:16
	v_mul_f32_e32 v4, 0x45800000, v3
	v_cndmask_b32_e32 v4, v3, v4, vcc
	v_pk_mul_f32 v[16:17], v[58:59], v[4:5] op_sel_hi:[1,0]
	v_pk_mul_f32 v[24:25], v[62:63], v[4:5] op_sel_hi:[1,0]
	v_pk_mul_f32 v[26:27], v[70:71], v[4:5] op_sel_hi:[1,0]
	v_pk_mul_f32 v[40:41], v[74:75], v[4:5] op_sel_hi:[1,0]
	v_pk_mul_f32 v[42:43], v[84:85], v[4:5] op_sel_hi:[1,0]
	v_pk_mul_f32 v[44:45], v[80:81], v[4:5] op_sel_hi:[1,0]
	v_pk_mul_f32 v[46:47], v[56:57], v[4:5] op_sel_hi:[1,0]
	v_pk_mul_f32 v[18:19], v[18:19], v[4:5] op_sel_hi:[1,0]
	v_cvt_pk_bf16_f32 v8, v16, v17
	v_cvt_pk_bf16_f32 v9, v24, v25
	v_cvt_pk_bf16_f32 v10, v26, v27
	v_cvt_pk_bf16_f32 v11, v40, v41
	v_pk_mul_f32 v[4:5], v[0:1], v[16:17] op_sel_hi:[0,1]
	v_cvt_pk_bf16_f32 v12, v42, v43
	v_cvt_pk_bf16_f32 v13, v44, v45
	v_cvt_pk_bf16_f32 v14, v46, v47
	v_cvt_pk_bf16_f32 v15, v18, v19
	ds_write_b128 v102, v[8:11]
	ds_write_b128 v102, v[12:15] offset:16
	v_pk_mul_f32 v[8:9], v[2:3], v[4:5] op_sel_hi:[0,1]
	v_pk_mul_f32 v[4:5], v[0:1], v[24:25] op_sel_hi:[0,1]
	v_pk_mul_f32 v[10:11], v[2:3], v[4:5] op_sel_hi:[0,1]
	v_pk_mul_f32 v[4:5], v[0:1], v[26:27] op_sel_hi:[0,1]
	ds_write_b128 v64, v[8:11] offset:51712
	v_pk_mul_f32 v[8:9], v[2:3], v[4:5] op_sel_hi:[0,1]
	v_pk_mul_f32 v[4:5], v[0:1], v[40:41] op_sel_hi:[0,1]
	v_pk_mul_f32 v[10:11], v[2:3], v[4:5] op_sel_hi:[0,1]
	v_pk_mul_f32 v[4:5], v[0:1], v[42:43] op_sel_hi:[0,1]
	ds_write_b128 v64, v[8:11] offset:51728
	v_pk_mul_f32 v[8:9], v[2:3], v[4:5] op_sel_hi:[0,1]
	v_pk_mul_f32 v[4:5], v[0:1], v[44:45] op_sel_hi:[0,1]
	v_pk_mul_f32 v[10:11], v[2:3], v[4:5] op_sel_hi:[0,1]
	ds_write_b128 v64, v[8:11] offset:51744
	v_exp_f32_e32 v8, v6
	v_pk_mul_f32 v[4:5], v[0:1], v[46:47] op_sel_hi:[0,1]
	v_pk_mul_f32 v[6:7], v[0:1], v[18:19] op_sel_hi:[0,1]
	v_pk_mul_f32 v[4:5], v[2:3], v[4:5] op_sel_hi:[0,1]
	v_pk_mul_f32 v[6:7], v[2:3], v[6:7] op_sel_hi:[0,1]
; __device__ __forceinline__ bf16_t f2bf(float x) { return (bf16_t)(pk2(x, 0.f) & 0xffffu); }
; __device__ __forceinline__ void phase_chunk_prep(const Params& p, LAS unsigned char* lds, int wave_s) {
;     ...
;         for (int j = 0; j < 16; ++j) { RHS[r * 256 + seg * 16 + j] = v[j] * be_r; RHS[r * 256 + 128 + seg * 16 + j] = k[j] * be_r * eg; }
; #pragma unroll
;         for (int j = 0; j < 16; ++j) img[IMG_KT + (seg * 16 + j) * SKT + r] = f2bf(k[j] * et);
;         if (tid == 0) ((float*)(p.ws + WS_GL))[unit] = __expf(gc_last);
	v_mul_u32_u24_e32 v2, 0x44, v209
	v_add3_u32 v2, v67, v2, s59
	v_pk_mul_f32 v[28:29], v[28:29], v[0:1] op_sel_hi:[1,0]
	v_pk_mul_f32 v[30:31], v[30:31], v[0:1] op_sel_hi:[1,0]
	v_pk_mul_f32 v[34:35], v[34:35], v[0:1] op_sel_hi:[1,0]
	v_pk_mul_f32 v[22:23], v[22:23], v[0:1] op_sel_hi:[1,0]
	v_pk_mul_f32 v[36:37], v[92:93], v[0:1] op_sel_hi:[1,0]
	v_ashrrev_i32_e32 v3, 31, v2
	v_lshl_add_u64 v[2:3], v[2:3], 1, s[30:31]
	ds_write_b128 v64, v[28:31] offset:51200
	ds_write_b128 v64, v[32:35] offset:51216
	ds_write_b128 v64, v[20:23] offset:51232
	ds_write_b128 v64, v[36:39] offset:51248
	ds_write_b128 v64, v[4:7] offset:51760
	v_mul_f32_e32 v100, v8, v16
	v_mul_f32_e32 v101, v8, v17
	v_mul_f32_e32 v102, v8, v24
	v_mul_f32_e32 v103, v8, v25
	v_mul_f32_e32 v104, v8, v26
	v_mul_f32_e32 v105, v8, v27
	v_mul_f32_e32 v106, v8, v40
	v_mul_f32_e32 v107, v8, v41
	v_mul_f32_e32 v108, v8, v42
	v_mul_f32_e32 v109, v8, v43
	v_mul_f32_e32 v110, v8, v44
	v_mul_f32_e32 v111, v8, v45
	v_mul_f32_e32 v112, v8, v46
	v_mul_f32_e32 v113, v8, v47
	v_mul_f32_e32 v114, v8, v18
	v_mul_f32_e32 v115, v8, v19
	s_nop 0
	v_permlane32_swap_b32_e32 v100, v108
	v_permlane32_swap_b32_e32 v101, v109
	v_permlane32_swap_b32_e32 v102, v110
	v_permlane32_swap_b32_e32 v103, v111
	v_permlane32_swap_b32_e32 v104, v112
	v_permlane32_swap_b32_e32 v105, v113
	v_permlane32_swap_b32_e32 v106, v114
	v_permlane32_swap_b32_e32 v107, v115
	s_nop 0
	v_permlane16_swap_b32_e32 v100, v104
	v_permlane16_swap_b32_e32 v101, v105
	v_permlane16_swap_b32_e32 v102, v106
	v_permlane16_swap_b32_e32 v103, v107
	v_permlane16_swap_b32_e32 v108, v112
	v_permlane16_swap_b32_e32 v109, v113
	v_permlane16_swap_b32_e32 v110, v114
	v_permlane16_swap_b32_e32 v111, v115
	s_mov_b32 s34, 0xff00ff00
	s_mov_b32 s35, 0xff00ff00
	v_cndmask_b32_e64 v120, v102, v100, s[34:35]
	v_cndmask_b32_e64 v121, v103, v101, s[34:35]
	v_cndmask_b32_e64 v122, v106, v104, s[34:35]
	v_cndmask_b32_e64 v123, v107, v105, s[34:35]
	v_cndmask_b32_e64 v124, v110, v108, s[34:35]
	v_cndmask_b32_e64 v125, v111, v109, s[34:35]
	v_cndmask_b32_e64 v126, v114, v112, s[34:35]
	v_cndmask_b32_e64 v127, v115, v113, s[34:35]
	v_mov_b32_dpp v128, v120 row_ror:8 row_mask:0xf bank_mask:0xf
	v_mov_b32_dpp v129, v121 row_ror:8 row_mask:0xf bank_mask:0xf
	v_mov_b32_dpp v130, v122 row_ror:8 row_mask:0xf bank_mask:0xf
	v_mov_b32_dpp v131, v123 row_ror:8 row_mask:0xf bank_mask:0xf
	v_mov_b32_dpp v132, v124 row_ror:8 row_mask:0xf bank_mask:0xf
	v_mov_b32_dpp v133, v125 row_ror:8 row_mask:0xf bank_mask:0xf
	v_mov_b32_dpp v134, v126 row_ror:8 row_mask:0xf bank_mask:0xf
	v_mov_b32_dpp v135, v127 row_ror:8 row_mask:0xf bank_mask:0xf
	v_cndmask_b32_e64 v100, v100, v128, s[34:35]
	v_cndmask_b32_e64 v102, v128, v102, s[34:35]
	v_cndmask_b32_e64 v101, v101, v129, s[34:35]
	v_cndmask_b32_e64 v103, v129, v103, s[34:35]
	v_cndmask_b32_e64 v104, v104, v130, s[34:35]
	v_cndmask_b32_e64 v106, v130, v106, s[34:35]
	v_cndmask_b32_e64 v105, v105, v131, s[34:35]
	v_cndmask_b32_e64 v107, v131, v107, s[34:35]
	v_cndmask_b32_e64 v108, v108, v132, s[34:35]
	v_cndmask_b32_e64 v110, v132, v110, s[34:35]
	v_cndmask_b32_e64 v109, v109, v133, s[34:35]
	v_cndmask_b32_e64 v111, v133, v111, s[34:35]
	v_cndmask_b32_e64 v112, v112, v134, s[34:35]
	v_cndmask_b32_e64 v114, v134, v114, s[34:35]
	v_cndmask_b32_e64 v113, v113, v135, s[34:35]
	v_cndmask_b32_e64 v115, v135, v115, s[34:35]
	v_cvt_pk_bf16_f32 v140, v100, v102
	v_cvt_pk_bf16_f32 v141, v104, v106
	v_cvt_pk_bf16_f32 v142, v108, v110
	v_cvt_pk_bf16_f32 v143, v112, v114
	v_cvt_pk_bf16_f32 v144, v101, v103
	v_cvt_pk_bf16_f32 v145, v105, v107
	v_cvt_pk_bf16_f32 v146, v109, v111
	v_cvt_pk_bf16_f32 v147, v113, v115
	v_mbcnt_lo_u32_b32 v4, -1, 0
	v_mbcnt_hi_u32_b32 v4, -1, v4
	v_lshrrev_b32_e32 v4, 3, v4
	v_mul_u32_u24_e32 v4, 0x10e, v4
	v_mov_b32_e32 v5, 0
	v_lshl_add_u64 v[2:3], v[2:3], 0, v[4:5]
	global_store_dwordx2 v[2:3], v[140:141], off
	global_store_dwordx2 v[2:3], v[142:143], off offset:8
	global_store_dwordx2 v[2:3], v[144:145], off offset:136
	global_store_dwordx2 v[2:3], v[146:147], off offset:144
	v_cmp_eq_u32_e32 vcc, 0, v66
	s_and_saveexec_b64 s[4:5], vcc
	s_cbranch_execz .LBB0_685
	v_mul_f32_e32 v0, 0x3fb8aa3b, v1
	v_exp_f32_e32 v0, v0
	s_lshl_b64 s[34:35], s[16:17], 2
	s_add_u32 s34, s39, s34
	s_addc_u32 s35, s40, s35
	global_store_dword v65, v0, s[34:35]
